# RWKV prep: a-LoRA MFMAs no longer wait for the cold input loads (vmcnt drain deferred to first use)
# speedup vs baseline: 1.0175x; 1.0012x over previous
; __device__ __forceinline__ void rwkv_prep_tile(LAS unsigned char* lds, const PrepArgs& P, int tt, int tid) {
;     ...
;         { const bf16_t* Up = hp ? Ut - 1792 : Ut; const unsigned pm = hp ? 0xffffffffu : 0u;
; #pragma unroll
;           for (int n = 0; n < 4; ++n) { const int c = cb + 16 * n + fq4;
;               uk[n] = *(const u32x2*)(Ut + 512 + c); ur[n] = *(const u32x2*)(Ut + c); uv[n] = *(const u32x2*)(Ut + 1024 + c);
;               pk[n] = *(const u32x2*)(Up + 512 + c); pr[n] = *(const u32x2*)(Up + c); pv[n] = *(const u32x2*)(Up + 1024 + c);
;               if (P.layer > 0) vf[n] = *(const f32x4*)(P.vfirst + (size_t)(t0 + i) * 512 + c); }
; #pragma unroll
;           for (int n = 0; n < 4; ++n) { pk[n].x &= pm; pk[n].y &= pm; pr[n].x &= pm; pr[n].y &= pm; pv[n].x &= pm; pv[n].y &= pm; } }
;         f32x4 aa[4], acc[4];
;         row_gemm<64>(aa, LAa + i * SW, P.a2t + (size_t)cb * 64, fr, fq);
;         row_gemm<64>(acc, LAw + i * SW, P.w2t + (size_t)cb * 64, fr, fq);
.Lp4_skip_p:
	ds_read_b128 v[18:21], v215
	ds_read_b128 v[22:25], v215 offset:2048
	ds_read_b128 v[26:29], v215 offset:4096
	v_add_u32_e32 v62, v212, v208
	ds_read_b128 v[34:37], v62 offset:9216
	ds_read_b128 v[30:33], v62 offset:9280
	ds_read_b128 v[38:41], v215 offset:1024
	ds_read_b128 v[42:45], v215 offset:5120
	ds_read_b128 v[46:49], v215 offset:3072
	v_lshlrev_b32_e32 v162, 2, v98
	v_add_u32_e32 v71, s34, v162
	v_lshl_add_u64 v[88:89], v[156:157], 0, s[10:11]
	v_ashrrev_i32_e32 v163, 31, v162
	s_mov_b32 s24, 0xe100000
	v_ashrrev_i32_e32 v99, 31, v98
	s_waitcnt lgkmcnt(4)
	v_mfma_f32_16x16x32_bf16 v[18:21], v[18:21], v[34:37], 0
	s_waitcnt lgkmcnt(5)
	v_mfma_f32_16x16x32_bf16 v[54:57], v[26:29], v[34:37], 0
	v_mfma_f32_16x16x32_bf16 v[22:25], v[22:25], v[34:37], 0
	s_waitcnt lgkmcnt(1)
	v_mfma_f32_16x16x32_bf16 v[34:37], v[42:45], v[34:37], 0
	s_waitcnt lgkmcnt(0)
	v_mfma_f32_16x16x32_bf16 v[22:25], v[46:49], v[30:33], v[22:25]
	s_waitcnt lgkmcnt(0)
	s_waitcnt lgkmcnt(0)
	s_and_b64 vcc, exec, s[4:5]
	s_waitcnt lgkmcnt(0)
	s_waitcnt vmcnt(0) lgkmcnt(0)
	s_cmp_eq_u32 s35, 0
	s_cbranch_scc1 .Lp4_carry
	v_mov_b32_dpp v166, v128 row_ror:1 row_mask:0xf bank_mask:0x1
	v_mov_b32_dpp v167, v129 row_ror:1 row_mask:0xf bank_mask:0x1
	v_mov_b32_dpp v170, v130 row_ror:1 row_mask:0xf bank_mask:0x1
	v_mov_b32_dpp v171, v131 row_ror:1 row_mask:0xf bank_mask:0x1
	v_mov_b32_dpp v194, v132 row_ror:1 row_mask:0xf bank_mask:0x1
	v_mov_b32_dpp v195, v133 row_ror:1 row_mask:0xf bank_mask:0x1
	v_mov_b32_dpp v180, v134 row_ror:1 row_mask:0xf bank_mask:0x1
	v_mov_b32_dpp v181, v135 row_ror:1 row_mask:0xf bank_mask:0x1
	v_mov_b32_dpp v200, v136 row_ror:1 row_mask:0xf bank_mask:0x1
	v_mov_b32_dpp v201, v137 row_ror:1 row_mask:0xf bank_mask:0x1
	v_mov_b32_dpp v202, v138 row_ror:1 row_mask:0xf bank_mask:0x1
	v_mov_b32_dpp v203, v139 row_ror:1 row_mask:0xf bank_mask:0x1
	v_mov_b32_dpp v198, v140 row_ror:1 row_mask:0xf bank_mask:0x1
	v_mov_b32_dpp v199, v141 row_ror:1 row_mask:0xf bank_mask:0x1
	v_mov_b32_dpp v182, v142 row_ror:1 row_mask:0xf bank_mask:0x1
	v_mov_b32_dpp v183, v143 row_ror:1 row_mask:0xf bank_mask:0x1
	v_mov_b32_dpp v72, v144 row_ror:1 row_mask:0xf bank_mask:0x1
	v_mov_b32_dpp v73, v145 row_ror:1 row_mask:0xf bank_mask:0x1
	v_mov_b32_dpp v84, v146 row_ror:1 row_mask:0xf bank_mask:0x1
	v_mov_b32_dpp v85, v147 row_ror:1 row_mask:0xf bank_mask:0x1
	v_mov_b32_dpp v92, v148 row_ror:1 row_mask:0xf bank_mask:0x1
	v_mov_b32_dpp v93, v149 row_ror:1 row_mask:0xf bank_mask:0x1
	v_mov_b32_dpp v100, v150 row_ror:1 row_mask:0xf bank_mask:0x1
	v_mov_b32_dpp v101, v151 row_ror:1 row_mask:0xf bank_mask:0x1
	v_mov_b32_dpp v166, v164 row_shr:1 row_mask:0xf bank_mask:0xf
	v_mov_b32_dpp v167, v165 row_shr:1 row_mask:0xf bank_mask:0xf
	v_mov_b32_dpp v170, v168 row_shr:1 row_mask:0xf bank_mask:0xf
	v_mov_b32_dpp v171, v169 row_shr:1 row_mask:0xf bank_mask:0xf
	v_mov_b32_dpp v194, v176 row_shr:1 row_mask:0xf bank_mask:0xf
	v_mov_b32_dpp v195, v177 row_shr:1 row_mask:0xf bank_mask:0xf
	v_mov_b32_dpp v180, v172 row_shr:1 row_mask:0xf bank_mask:0xf
	v_mov_b32_dpp v181, v173 row_shr:1 row_mask:0xf bank_mask:0xf
	v_mov_b32_dpp v200, v196 row_shr:1 row_mask:0xf bank_mask:0xf
	v_mov_b32_dpp v201, v197 row_shr:1 row_mask:0xf bank_mask:0xf
	v_mov_b32_dpp v202, v184 row_shr:1 row_mask:0xf bank_mask:0xf
	v_mov_b32_dpp v203, v185 row_shr:1 row_mask:0xf bank_mask:0xf
	v_mov_b32_dpp v198, v178 row_shr:1 row_mask:0xf bank_mask:0xf
	v_mov_b32_dpp v199, v179 row_shr:1 row_mask:0xf bank_mask:0xf
	v_mov_b32_dpp v182, v174 row_shr:1 row_mask:0xf bank_mask:0xf
	v_mov_b32_dpp v183, v175 row_shr:1 row_mask:0xf bank_mask:0xf
	v_mov_b32_dpp v72, v74 row_shr:1 row_mask:0xf bank_mask:0xf
	v_mov_b32_dpp v73, v75 row_shr:1 row_mask:0xf bank_mask:0xf
	v_mov_b32_dpp v84, v86 row_shr:1 row_mask:0xf bank_mask:0xf
	v_mov_b32_dpp v85, v87 row_shr:1 row_mask:0xf bank_mask:0xf
	v_mov_b32_dpp v92, v104 row_shr:1 row_mask:0xf bank_mask:0xf
	v_mov_b32_dpp v93, v105 row_shr:1 row_mask:0xf bank_mask:0xf
	v_mov_b32_dpp v100, v102 row_shr:1 row_mask:0xf bank_mask:0xf
	v_mov_b32_dpp v101, v103 row_shr:1 row_mask:0xf bank_mask:0xf
